# final LayerNorm with one row of load look-ahead (next row's 8 loads issued before the current row is reduced), on top of the merge counted wait
# baseline (speedup 1.0000x reference)
; __global__ void __launch_bounds__(512, 2) fwd_megakernel(Params p) {
;     ...
;         switch (ph) {
;         case 0: if (EN(0)) prep_phase(p, smem); break;
;         case 1: gd.A = (const bf16_t*)(ws + OFF_B1); gd.Bt = (const bf16_t*)(ws + OFF_WIN); gd.C = ws + OFF_H; gd.rope = (const float*)(ws + OFF_ROPE); gd.aux = (float*)(ws + OFF_EB); gd.M = T_TOK; gd.N = HC; gd.K = DM; gd.ldc = HC; gd.mode = 1; break;
;         case 2:
;             if (bid < 64) { if (EN(1) && !(rep == 1 && REP_MODE == 2)) gla_item(p, bid, lds); }
;             else if (bid < 128 && !(rep == 1 && REP_MODE != 0)) { gd.A = (const bf16_t*)(ws + OFF_MEMB); gd.Bt = (const bf16_t*)(ws + OFF_WKV); gd.C = ws + OFF_MKV; gd.M = 1024; gd.N = 4096; gd.K = DM; gd.ldc = 4096; gd.mode = 0; gd.G = 64; gd.c = bid - 64; }
;             break;
;         case 3: if (EN(2)) merge_phase(p); break;
;         case 4: gd.A = (const bf16_t*)(ws + OFF_B1); gd.Bt = (const bf16_t*)(ws + OFF_WOUT); gd.C = ws + OFF_MIX4; gd.M = T_TOK; gd.N = DM; gd.K = DM; gd.ldc = DM; gd.mode = 0; break;
;         case 5: if (EN(3)) ln_phase2((const bf16_t*)(ws + OFF_MIX4), p.x, nullptr, p.ln1_g, p.ln1_b, (bf16_t*)(ws + OFF_X1B), nullptr); break;
;         case 6: gd.A = (const bf16_t*)(ws + OFF_X1B); gd.Bt = (const bf16_t*)(ws + OFF_WQ); gd.C = ws + OFF_B1; gd.M = T_TOK; gd.N = DM; gd.K = DM; gd.ldc = DM; gd.mode = 0; gd.order = 1; break;
;         case 7: break;
;         case 8: gd.A = (const bf16_t*)(ws + OFF_OC); gd.Bt = (const bf16_t*)(ws + OFF_WO); gd.C = ws + OFF_MIX8; gd.M = T_TOK; gd.N = DM; gd.K = DM; gd.ldc = DM; gd.mode = 0; break;
;         case 9: if (EN(3)) ln_phase2((const bf16_t*)(ws + OFF_MIX8), nullptr, (const bf16_t*)(ws + OFF_X1B), p.ln2_g, p.ln2_b, (bf16_t*)(ws + OFF_B1), nullptr); if (EN(5)) ffn_weights(p, smem); break;
;         case 10: gd.A = (const bf16_t*)(ws + OFF_B1); gd.Bt = (const bf16_t*)(ws + OFF_WF1); gd.C = ws + OFF_G; gd.R = p.conv_w; gd.rope = p.conv_b; gd.aux = (float*)(ws + OFF_U);
;             gd.M = T_TOK; gd.N = 11008; gd.K = DM; gd.ldc = DFF; gd.mode = 3; break;
;         case 11: if (EN(6)) conv_fixup(p); break;
;         case 12: gd.A = (const bf16_t*)(ws + OFF_G); gd.Bt = (const bf16_t*)(ws + OFF_WF2); gd.C = ws + OFF_MIX12; gd.M = T_TOK; gd.N = DM; gd.K = DFF; gd.ldc = DM; gd.mode = 0; break;
.LBB0_24:
	v_readlane_b32 s0, v254, 39
	s_cmp_lt_i32 s0, 6
	s_mov_b64 s[10:11], -1
	s_mov_b64 s[96:97], 0
	s_mov_b64 s[4:5], 0
	s_cbranch_scc1 .LBB0_87
	v_readlane_b32 s0, v254, 39
	s_cmp_gt_i32 s0, 9
	s_mov_b64 s[8:9], 0
	s_cbranch_scc0 .LBB0_51
	v_readlane_b32 s2, v254, 39
	s_mov_b64 s[0:1], -1
	s_mov_b64 s[50:51], 0
	s_cmp_gt_i32 s2, 11
	s_mov_b64 s[4:5], 0
	s_cbranch_scc0 .LBB0_38
	v_readlane_b32 s0, v254, 39
	s_mov_b64 s[6:7], -1
	s_cmp_gt_i32 s0, 12
	s_mov_b64 s[0:1], -1
	s_cbranch_scc0 .LBB0_34
	v_readlane_b32 s0, v254, 39
	s_cmp_eq_u32 s0, 13
	s_mov_b64 s[4:5], -1
	v_readlane_b32 s10, v251, 14
	s_movk_i32 s11, 0x1000
	s_mov_b32 s12, 0x800000
	s_movk_i32 s13, 0x3fff
	s_cbranch_scc0 .LBB0_33
	v_mov_b32_e32 v1, v212
	v_readlane_b32 s0, v252, 9
	v_ashrrev_i32_e32 v0, 6, v1
	s_nop 0
	v_add_u32_e32 v0, s0, v0
	s_movk_i32 s0, 0x4000
	v_cmp_gt_i32_e32 vcc, s0, v0
	s_and_saveexec_b64 s[0:1], vcc
	s_mov_b32 s4, 0x3f9837f0
	s_cbranch_execz .LBB0_32
	v_lshlrev_b32_e32 v1, 3, v1
	v_and_b32_e32 v84, 0x1f8, v1
	v_readlane_b32 s36, v251, 0
	v_lshlrev_b32_e32 v2, 2, v84
	v_readlane_b32 s42, v251, 6
	v_readlane_b32 s43, v251, 7
	s_nop 4
	global_load_dwordx4 v[4:7], v2, s[42:43] offset:16
	global_load_dwordx4 v[8:11], v2, s[42:43]
	global_load_dwordx4 v[12:15], v2, s[88:89] offset:16
	global_load_dwordx4 v[16:19], v2, s[88:89]
	global_load_dwordx4 v[20:23], v2, s[42:43] offset:2064
	global_load_dwordx4 v[24:27], v2, s[42:43] offset:2048
	global_load_dwordx4 v[28:31], v2, s[88:89] offset:2064
	global_load_dwordx4 v[32:35], v2, s[88:89] offset:2048
	v_lshl_add_u64 v[52:53], s[42:43], 0, v[2:3]
	v_add_co_u32_e32 v54, vcc, s11, v52
	v_lshl_add_u64 v[60:61], s[88:89], 0, v[2:3]
	s_mov_b64 s[2:3], 0x1000
	v_addc_co_u32_e32 v55, vcc, 0, v53, vcc
	v_lshl_add_u64 v[40:41], v[52:53], 0, s[2:3]
	v_lshl_add_u64 v[48:49], v[60:61], 0, s[2:3]
	v_add_co_u32_e32 v62, vcc, s11, v60
	s_mov_b64 s[2:3], 0x1800
	s_nop 0
	v_addc_co_u32_e32 v63, vcc, 0, v61, vcc
	v_lshl_add_u64 v[56:57], v[52:53], 0, s[2:3]
	v_lshl_add_u64 v[64:65], v[60:61], 0, s[2:3]
	global_load_dwordx4 v[36:39], v[54:55], off
	s_nop 0
	global_load_dwordx4 v[40:43], v[40:41], off offset:16
	s_nop 0
	global_load_dwordx4 v[44:47], v[62:63], off
	s_nop 0
	global_load_dwordx4 v[48:51], v[48:49], off offset:16
	s_nop 0
	global_load_dwordx4 v[52:55], v[54:55], off offset:2048
	s_nop 0
	global_load_dwordx4 v[56:59], v[56:57], off offset:16
	s_nop 0
	global_load_dwordx4 v[60:63], v[62:63], off offset:2048
	s_nop 0
	global_load_dwordx4 v[64:67], v[64:65], off offset:16
	v_cmp_lt_i32_e32 vcc, v217, v216
	v_readlane_b32 s38, v251, 2
	v_readlane_b32 s26, v254, 15
	v_cndmask_b32_e32 v1, v215, v217, vcc
	v_cmp_lt_i32_e32 vcc, v218, v216
	v_lshlrev_b32_e32 v2, 2, v1
	v_readlane_b32 s38, v254, 19
	v_cndmask_b32_e32 v1, v215, v218, vcc
	v_lshlrev_b32_e32 v85, 2, v1
	v_xor_b32_e32 v1, 8, v215
	v_cmp_lt_i32_e32 vcc, v1, v216
	v_readlane_b32 s27, v254, 16
	s_mov_b64 s[2:3], 0
	v_cndmask_b32_e32 v1, v215, v1, vcc
	v_lshlrev_b32_e32 v106, 2, v1
	v_xor_b32_e32 v1, 4, v215
	v_cmp_lt_i32_e32 vcc, v1, v216
	v_readlane_b32 s37, v251, 1
	v_readlane_b32 s39, v251, 3
	v_cndmask_b32_e32 v1, v215, v1, vcc
	v_lshlrev_b32_e32 v107, 2, v1
	v_xor_b32_e32 v1, 2, v215
	v_cmp_lt_i32_e32 vcc, v1, v216
	v_readlane_b32 s40, v251, 4
	v_readlane_b32 s41, v251, 5
	v_cndmask_b32_e32 v1, v215, v1, vcc
	v_cmp_lt_i32_e32 vcc, v250, v216
	v_lshlrev_b32_e32 v108, 2, v1
	s_nop 0
	v_cndmask_b32_e32 v1, v215, v250, vcc
	v_lshlrev_b32_e32 v109, 2, v1
	v_min_u32_e32 v176, 0x3fff, v0
	v_lshlrev_b32_e32 v176, 12, v176
	v_lshl_or_b32 v176, v84, 1, v176
	global_load_dwordx4 v[144:147], v176, s[68:69] nt
	global_load_dwordx4 v[148:151], v176, s[92:93] nt
	global_load_dwordx4 v[152:155], v176, s[68:69] offset:1024 nt
	global_load_dwordx4 v[156:159], v176, s[92:93] offset:1024 nt
	global_load_dwordx4 v[160:163], v176, s[68:69] offset:2048 nt
	global_load_dwordx4 v[164:167], v176, s[92:93] offset:2048 nt
	global_load_dwordx4 v[168:171], v176, s[68:69] offset:3072 nt
	global_load_dwordx4 v[172:175], v176, s[92:93] offset:3072 nt
	s_waitcnt vmcnt(0)
.LBB0_31:
	v_ashrrev_i32_e32 v1, 31, v0
	v_lshlrev_b64 v[88:89], 11, v[0:1]
	v_or_b32_e32 v88, v88, v84
	v_lshlrev_b64 v[68:69], 1, v[88:89]
	v_lshl_add_u64 v[70:71], s[68:69], 0, v[68:69]
	v_lshl_add_u64 v[72:73], s[92:93], 0, v[68:69]
	s_waitcnt vmcnt(8)
; __device__ __forceinline__ float bflo(unsigned u) { return __uint_as_float(u << 16); }
; __device__ __forceinline__ float bfhi(unsigned u) { return __uint_as_float(u & 0xffff0000u); }
; __device__ void ln_phase2(const bf16_t* __restrict__ mix, const float* __restrict__ Rf, const bf16_t* __restrict__ Rb, const float* __restrict__ gam, const float* __restrict__ bet, bf16_t* ob, float* of) {
;     ...
;     for (int row = blockIdx.x * 8 + wid; row < T_TOK; row += gridDim.x * 8) {
;         const size_t ro = (size_t)row * DM + lane * 8;
;         float v[32]; float s = 0.f;
; #pragma unroll
;         for (int j = 0; j < 4; ++j) {
;             const u32x4 m = *(const u32x4*)(mix + ro + 512 * j);
;             float r[8];
;             if (Rf) { const f32x4 a = *(const f32x4*)(Rf + ro + 512 * j), b = *(const f32x4*)(Rf + ro + 512 * j + 4);
;                 r[0] = a[0]; r[1] = a[1]; r[2] = a[2]; r[3] = a[3]; r[4] = b[0]; r[5] = b[1]; r[6] = b[2]; r[7] = b[3]; }
;             else { const u32x4 rb = *(const u32x4*)(Rb + ro + 512 * j);
;                 r[0] = bflo(rb.x); r[1] = bfhi(rb.x); r[2] = bflo(rb.y); r[3] = bfhi(rb.y); r[4] = bflo(rb.z); r[5] = bfhi(rb.z); r[6] = bflo(rb.w); r[7] = bfhi(rb.w); }
;             v[8 * j + 0] = DN_ALPHA * r[0] + bflo(m.x); v[8 * j + 1] = DN_ALPHA * r[1] + bfhi(m.x); v[8 * j + 2] = DN_ALPHA * r[2] + bflo(m.y); v[8 * j + 3] = DN_ALPHA * r[3] + bfhi(m.y);
;             v[8 * j + 4] = DN_ALPHA * r[4] + bflo(m.z); v[8 * j + 5] = DN_ALPHA * r[5] + bfhi(m.z); v[8 * j + 6] = DN_ALPHA * r[6] + bflo(m.w); v[8 * j + 7] = DN_ALPHA * r[7] + bfhi(m.w);
; #pragma unroll
;             for (int e = 0; e < 8; ++e) s += v[8 * j + e];
;         }
; #pragma unroll
;         for (int o = 32; o; o >>= 1) s += __shfl_xor(s, o);
	v_mov_b64_e32 v[94:95], v[144:145]
	v_mov_b64_e32 v[96:97], v[146:147]
	v_mov_b64_e32 v[98:99], v[148:149]
	v_mov_b64_e32 v[100:101], v[150:151]
	v_mov_b64_e32 v[110:111], v[152:153]
	v_mov_b64_e32 v[112:113], v[154:155]
	v_mov_b64_e32 v[114:115], v[156:157]
	v_mov_b64_e32 v[116:117], v[158:159]
	v_mov_b64_e32 v[76:77], v[160:161]
	v_mov_b64_e32 v[78:79], v[162:163]
	v_mov_b64_e32 v[80:81], v[164:165]
	v_mov_b64_e32 v[82:83], v[166:167]
	s_nop 0
	v_mov_b64_e32 v[68:69], v[168:169]
	v_mov_b64_e32 v[70:71], v[170:171]
	s_nop 0
	v_mov_b64_e32 v[72:73], v[172:173]
	v_mov_b64_e32 v[74:75], v[174:175]
	v_add_u32_e32 v0, s10, v0
	v_min_u32_e32 v176, 0x3fff, v0
	v_lshlrev_b32_e32 v176, 12, v176
	v_lshl_or_b32 v176, v84, 1, v176
	global_load_dwordx4 v[144:147], v176, s[68:69] nt
	global_load_dwordx4 v[148:151], v176, s[92:93] nt
	global_load_dwordx4 v[152:155], v176, s[68:69] offset:1024 nt
	global_load_dwordx4 v[156:159], v176, s[92:93] offset:1024 nt
	global_load_dwordx4 v[160:163], v176, s[68:69] offset:2048 nt
	global_load_dwordx4 v[164:167], v176, s[92:93] offset:2048 nt
	global_load_dwordx4 v[168:171], v176, s[68:69] offset:3072 nt
	global_load_dwordx4 v[172:175], v176, s[92:93] offset:3072 nt
	v_lshlrev_b32_e32 v92, 16, v97
	v_and_b32_e32 v93, 0xffff0000, v97
	v_and_b32_e32 v97, 0xffff0000, v94
	v_lshlrev_b32_e32 v102, 16, v110
	v_and_b32_e32 v103, 0xffff0000, v110
	v_lshlrev_b32_e32 v104, 16, v111
	v_and_b32_e32 v90, 0xffff0000, v70
	v_and_b32_e32 v86, 0xffff0000, v74
	v_lshlrev_b32_e32 v87, 16, v74
	v_lshlrev_b32_e32 v91, 16, v70
	v_and_b32_e32 v74, 0xffff0000, v75
	v_lshlrev_b32_e32 v75, 16, v75
	v_and_b32_e32 v70, 0xffff0000, v71
	v_lshlrev_b32_e32 v71, 16, v71
	v_pk_fma_f32 v[86:87], v[86:87], s[4:5], v[90:91] op_sel_hi:[1,0,1]
	v_pk_fma_f32 v[74:75], v[74:75], s[4:5], v[70:71] op_sel_hi:[1,0,1]
	v_lshl_add_u64 v[70:71], v[88:89], 2, s[90:91]
	v_lshlrev_b32_e32 v88, 16, v100
	v_and_b32_e32 v89, 0xffff0000, v100
	v_lshlrev_b32_e32 v90, 16, v96
	v_and_b32_e32 v91, 0xffff0000, v96
	v_pk_fma_f32 v[88:89], v[88:89], s[4:5], v[90:91] op_sel_hi:[1,0,1]
	v_lshlrev_b32_e32 v90, 16, v101
	v_and_b32_e32 v91, 0xffff0000, v101
	v_pk_fma_f32 v[90:91], v[90:91], s[4:5], v[92:93] op_sel_hi:[1,0,1]
	v_lshlrev_b32_e32 v92, 16, v98
	v_and_b32_e32 v93, 0xffff0000, v98
	v_lshlrev_b32_e32 v96, 16, v94
	v_pk_fma_f32 v[92:93], v[92:93], s[4:5], v[96:97] op_sel_hi:[1,0,1]
	v_lshlrev_b32_e32 v96, 16, v99
	v_add_f32_e32 v1, 0, v92
	v_and_b32_e32 v97, 0xffff0000, v99
	v_lshlrev_b32_e32 v94, 16, v95
	v_and_b32_e32 v95, 0xffff0000, v95
	v_add_f32_e32 v1, v93, v1
	v_pk_fma_f32 v[94:95], v[96:97], s[4:5], v[94:95] op_sel_hi:[1,0,1]
	v_lshlrev_b32_e32 v96, 16, v116
	v_add_f32_e32 v1, v94, v1
	v_add_f32_e32 v1, v95, v1
	v_add_f32_e32 v1, v88, v1
	v_and_b32_e32 v97, 0xffff0000, v116
	v_lshlrev_b32_e32 v98, 16, v112
	v_and_b32_e32 v99, 0xffff0000, v112
	v_add_f32_e32 v1, v89, v1
	v_pk_fma_f32 v[96:97], v[96:97], s[4:5], v[98:99] op_sel_hi:[1,0,1]
	v_lshlrev_b32_e32 v98, 16, v117
	v_and_b32_e32 v99, 0xffff0000, v117
	v_lshlrev_b32_e32 v100, 16, v113
	v_and_b32_e32 v101, 0xffff0000, v113
	v_add_f32_e32 v1, v90, v1
	v_pk_fma_f32 v[98:99], v[98:99], s[4:5], v[100:101] op_sel_hi:[1,0,1]
	v_lshlrev_b32_e32 v100, 16, v114
	v_and_b32_e32 v101, 0xffff0000, v114
	v_add_f32_e32 v1, v91, v1
	v_pk_fma_f32 v[102:103], v[100:101], s[4:5], v[102:103] op_sel_hi:[1,0,1]
	v_lshlrev_b32_e32 v100, 16, v115
	v_add_f32_e32 v1, v102, v1
	v_and_b32_e32 v101, 0xffff0000, v115
	v_and_b32_e32 v105, 0xffff0000, v111
	v_add_f32_e32 v1, v103, v1
	v_pk_fma_f32 v[104:105], v[100:101], s[4:5], v[104:105] op_sel_hi:[1,0,1]
	v_lshlrev_b32_e32 v100, 16, v82
	v_add_f32_e32 v1, v104, v1
	v_add_f32_e32 v1, v105, v1
	v_add_f32_e32 v1, v96, v1
	v_add_f32_e32 v1, v97, v1
	v_and_b32_e32 v101, 0xffff0000, v82
	v_lshlrev_b32_e32 v110, 16, v78
	v_and_b32_e32 v111, 0xffff0000, v78
	v_lshlrev_b32_e32 v82, 16, v83
	v_and_b32_e32 v83, 0xffff0000, v83
	v_lshlrev_b32_e32 v78, 16, v79
	v_and_b32_e32 v79, 0xffff0000, v79
	v_add_f32_e32 v1, v98, v1
	v_pk_fma_f32 v[100:101], v[100:101], s[4:5], v[110:111] op_sel_hi:[1,0,1]
	v_pk_fma_f32 v[78:79], v[82:83], s[4:5], v[78:79] op_sel_hi:[1,0,1]
	v_lshlrev_b32_e32 v82, 16, v80
	v_and_b32_e32 v83, 0xffff0000, v80
	v_lshlrev_b32_e32 v110, 16, v76
	v_and_b32_e32 v111, 0xffff0000, v76
	v_add_f32_e32 v1, v99, v1
	v_pk_fma_f32 v[82:83], v[82:83], s[4:5], v[110:111] op_sel_hi:[1,0,1]
	v_lshlrev_b32_e32 v80, 16, v81
	v_add_f32_e32 v1, v82, v1
	v_and_b32_e32 v81, 0xffff0000, v81
	v_lshlrev_b32_e32 v76, 16, v77
	v_and_b32_e32 v77, 0xffff0000, v77
	v_add_f32_e32 v1, v83, v1
	v_pk_fma_f32 v[76:77], v[80:81], s[4:5], v[76:77] op_sel_hi:[1,0,1]
	v_lshlrev_b32_e32 v80, 16, v72
	v_add_f32_e32 v1, v76, v1
	v_add_f32_e32 v1, v77, v1
	v_add_f32_e32 v1, v100, v1
	v_add_f32_e32 v1, v101, v1
	v_add_f32_e32 v1, v78, v1
	v_and_b32_e32 v81, 0xffff0000, v72
	v_lshlrev_b32_e32 v110, 16, v68
	v_and_b32_e32 v111, 0xffff0000, v68
	v_add_f32_e32 v1, v79, v1
	v_pk_fma_f32 v[80:81], v[80:81], s[4:5], v[110:111] op_sel_hi:[1,0,1]
	v_lshlrev_b32_e32 v72, 16, v73
	v_add_f32_e32 v1, v80, v1
	v_and_b32_e32 v73, 0xffff0000, v73
	v_lshlrev_b32_e32 v68, 16, v69
	v_and_b32_e32 v69, 0xffff0000, v69
	v_add_f32_e32 v1, v81, v1
	v_pk_fma_f32 v[68:69], v[72:73], s[4:5], v[68:69] op_sel_hi:[1,0,1]
	s_nop 0
	v_add_f32_e32 v1, v68, v1
	v_add_f32_e32 v1, v69, v1
	v_add_f32_e32 v1, v87, v1
	v_add_f32_e32 v1, v86, v1
	v_add_f32_e32 v1, v75, v1
	v_add_f32_e32 v1, v74, v1
	v_mov_b32_e32 v72, v1
	s_nop 1
	v_permlane32_swap_b32 v72, v1
	v_add_f32_e32 v1, v1, v72
	v_mov_b32_e32 v72, v1
	s_nop 1
	v_permlane16_swap_b32 v72, v1
; __device__ __forceinline__ unsigned cvt_pk_bf16(float lo, float hi) { const f32x2v v = {lo, hi}; const b16x2v r = __builtin_convertvector(v, b16x2v); return __builtin_bit_cast(unsigned, r); }
; __device__ void ln_phase2(const bf16_t* __restrict__ mix, const float* __restrict__ Rf, const bf16_t* __restrict__ Rb, const float* __restrict__ gam, const float* __restrict__ bet, bf16_t* ob, float* of) {
;     ...
;         const float mean = s * (1.0f / 2048.0f);
;         float q = 0.f;
; #pragma unroll
;         for (int e = 0; e < 32; ++e) { const float dlt = v[e] - mean; q += dlt * dlt; }
; #pragma unroll
;         for (int o = 32; o; o >>= 1) q += __shfl_xor(q, o);
;         const float rstd = rsqrtf(q * (1.0f / 2048.0f) + 1e-5f);
; #pragma unroll
;         for (int j = 0; j < 4; ++j) {
;             const f32x4 g0 = *(const f32x4*)(gam + lane * 8 + 512 * j), g1 = *(const f32x4*)(gam + lane * 8 + 512 * j + 4);
;             const f32x4 b0 = *(const f32x4*)(bet + lane * 8 + 512 * j), b1 = *(const f32x4*)(bet + lane * 8 + 512 * j + 4);
;             f32x4 y0, y1;
; #pragma unroll
;             for (int e = 0; e < 4; ++e) { y0[e] = (v[8 * j + e] - mean) * rstd * g0[e] + b0[e]; y1[e] = (v[8 * j + 4 + e] - mean) * rstd * g1[e] + b1[e]; }
;             if (ob) { u32x4 w; w.x = cvt_pk_bf16(y0[0], y0[1]); w.y = cvt_pk_bf16(y0[2], y0[3]); w.z = cvt_pk_bf16(y1[0], y1[1]); w.w = cvt_pk_bf16(y1[2], y1[3]); *(u32x4*)(ob + ro + 512 * j) = w; }
;             else { *(f32x4*)(of + ro + 512 * j) = y0; *(f32x4*)(of + ro + 512 * j + 4) = y1; }
	v_add_f32_e32 v1, v1, v72
	s_nop 1
	v_add_f32_dpp v1, v1, v1 quad_perm:[1,0,3,2] row_mask:0xf bank_mask:0xf
	s_nop 1
	v_add_f32_dpp v1, v1, v1 quad_perm:[2,3,0,1] row_mask:0xf bank_mask:0xf
	s_nop 1
	v_add_f32_dpp v1, v1, v1 row_half_mirror row_mask:0xf bank_mask:0xf
	s_nop 1
	v_add_f32_dpp v1, v1, v1 row_mirror row_mask:0xf bank_mask:0xf
	v_mul_f32_e32 v72, 0x3a000000, v1
	v_pk_add_f32 v[92:93], v[92:93], v[72:73] op_sel_hi:[1,0] neg_lo:[0,1] neg_hi:[0,1]
	v_pk_add_f32 v[94:95], v[94:95], v[72:73] op_sel_hi:[1,0] neg_lo:[0,1] neg_hi:[0,1]
	v_pk_mul_f32 v[110:111], v[92:93], v[92:93]
	v_pk_mul_f32 v[112:113], v[94:95], v[94:95]
	v_add_f32_e32 v1, v110, v111
	v_pk_add_f32 v[88:89], v[88:89], v[72:73] op_sel_hi:[1,0] neg_lo:[0,1] neg_hi:[0,1]
	v_add_f32_e32 v1, v112, v1
	v_pk_mul_f32 v[114:115], v[88:89], v[88:89]
	v_add_f32_e32 v1, v113, v1
	v_pk_add_f32 v[90:91], v[90:91], v[72:73] op_sel_hi:[1,0] neg_lo:[0,1] neg_hi:[0,1]
	v_add_f32_e32 v1, v114, v1
	v_pk_mul_f32 v[116:117], v[90:91], v[90:91]
	v_add_f32_e32 v1, v115, v1
	v_pk_add_f32 v[102:103], v[102:103], v[72:73] op_sel_hi:[1,0] neg_lo:[0,1] neg_hi:[0,1]
	v_add_f32_e32 v1, v116, v1
	v_pk_mul_f32 v[118:119], v[102:103], v[102:103]
	v_add_f32_e32 v1, v117, v1
	v_pk_add_f32 v[104:105], v[104:105], v[72:73] op_sel_hi:[1,0] neg_lo:[0,1] neg_hi:[0,1]
	v_add_f32_e32 v1, v118, v1
	v_pk_mul_f32 v[120:121], v[104:105], v[104:105]
	v_add_f32_e32 v1, v119, v1
	v_pk_add_f32 v[96:97], v[96:97], v[72:73] op_sel_hi:[1,0] neg_lo:[0,1] neg_hi:[0,1]
	v_add_f32_e32 v1, v120, v1
	v_pk_mul_f32 v[122:123], v[96:97], v[96:97]
	v_add_f32_e32 v1, v121, v1
	v_pk_add_f32 v[98:99], v[98:99], v[72:73] op_sel_hi:[1,0] neg_lo:[0,1] neg_hi:[0,1]
	v_add_f32_e32 v1, v122, v1
	v_pk_mul_f32 v[124:125], v[98:99], v[98:99]
	v_add_f32_e32 v1, v123, v1
	v_pk_add_f32 v[82:83], v[82:83], v[72:73] op_sel_hi:[1,0] neg_lo:[0,1] neg_hi:[0,1]
	v_add_f32_e32 v1, v124, v1
	v_pk_mul_f32 v[126:127], v[82:83], v[82:83]
	v_add_f32_e32 v1, v125, v1
	v_pk_add_f32 v[128:129], v[76:77], v[72:73] op_sel_hi:[1,0] neg_lo:[0,1] neg_hi:[0,1]
	v_add_f32_e32 v1, v126, v1
	v_pk_mul_f32 v[76:77], v[128:129], v[128:129]
	v_add_f32_e32 v1, v127, v1
	v_pk_add_f32 v[100:101], v[100:101], v[72:73] op_sel_hi:[1,0] neg_lo:[0,1] neg_hi:[0,1]
	v_add_f32_e32 v1, v76, v1
	v_pk_mul_f32 v[130:131], v[100:101], v[100:101]
	v_add_f32_e32 v1, v77, v1
	v_pk_add_f32 v[132:133], v[78:79], v[72:73] op_sel_hi:[1,0] neg_lo:[0,1] neg_hi:[0,1]
	v_add_f32_e32 v1, v130, v1
	v_pk_mul_f32 v[78:79], v[132:133], v[132:133]
	v_add_f32_e32 v1, v131, v1
	v_pk_add_f32 v[80:81], v[80:81], v[72:73] op_sel_hi:[1,0] neg_lo:[0,1] neg_hi:[0,1]
	v_add_f32_e32 v1, v78, v1
	v_pk_mul_f32 v[134:135], v[80:81], v[80:81]
	v_add_f32_e32 v1, v79, v1
	v_pk_add_f32 v[136:137], v[68:69], v[72:73] op_sel_hi:[1,0] neg_lo:[0,1] neg_hi:[0,1]
	v_add_f32_e32 v1, v134, v1
	v_pk_mul_f32 v[68:69], v[136:137], v[136:137]
	v_add_f32_e32 v1, v135, v1
	v_pk_add_f32 v[86:87], v[86:87], v[72:73] op_sel_hi:[1,0] neg_lo:[0,1] neg_hi:[0,1]
	v_add_f32_e32 v1, v68, v1
	v_pk_mul_f32 v[138:139], v[86:87], v[86:87]
	v_add_f32_e32 v1, v69, v1
	v_pk_add_f32 v[140:141], v[74:75], v[72:73] op_sel_hi:[1,0] neg_lo:[0,1] neg_hi:[0,1]
	v_add_f32_e32 v1, v139, v1
	v_pk_mul_f32 v[72:73], v[140:141], v[140:141]
	v_add_f32_e32 v1, v138, v1
	v_add_f32_e32 v1, v73, v1
	v_add_f32_e32 v1, v72, v1
	v_mov_b32_e32 v68, v1
	s_nop 1
	v_permlane32_swap_b32 v68, v1
	v_add_f32_e32 v1, v1, v68
	v_mov_b32_e32 v68, v1
	s_nop 1
	v_permlane16_swap_b32 v68, v1
	v_add_f32_e32 v1, v1, v68
	s_nop 1
	v_add_f32_dpp v1, v1, v1 quad_perm:[1,0,3,2] row_mask:0xf bank_mask:0xf
	s_nop 1
	v_add_f32_dpp v1, v1, v1 quad_perm:[2,3,0,1] row_mask:0xf bank_mask:0xf
	s_nop 1
	v_add_f32_dpp v1, v1, v1 row_half_mirror row_mask:0xf bank_mask:0xf
	s_nop 1
	v_add_f32_dpp v1, v1, v1 row_mirror row_mask:0xf bank_mask:0xf
	v_fmamk_f32 v1, v1, 0x3a000000, v213
	v_cmp_gt_f32_e32 vcc, s12, v1
	v_mul_f32_e32 v68, 0x4b800000, v1
	s_nop 0
	v_cndmask_b32_e32 v1, v1, v68, vcc
	v_rsq_f32_e32 v1, v1
	s_nop 0
	v_mul_f32_e32 v68, 0x45800000, v1
	v_cndmask_b32_e32 v110, v1, v68, vcc
	v_pk_mul_f32 v[68:69], v[92:93], v[110:111] op_sel_hi:[1,0]
	v_pk_mul_f32 v[72:73], v[94:95], v[110:111] op_sel_hi:[1,0]
	v_pk_mul_f32 v[76:77], v[90:91], v[110:111] op_sel_hi:[1,0]
	v_pk_fma_f32 v[74:75], v[10:11], v[72:73], v[18:19]
	v_pk_fma_f32 v[72:73], v[8:9], v[68:69], v[16:17]
	v_pk_mul_f32 v[68:69], v[88:89], v[110:111] op_sel_hi:[1,0]
	v_pk_fma_f32 v[78:79], v[6:7], v[76:77], v[14:15]
	v_pk_fma_f32 v[76:77], v[4:5], v[68:69], v[12:13]
	global_store_dwordx4 v[70:71], v[72:75], off nt
	global_store_dwordx4 v[70:71], v[76:79], off offset:16 nt
	v_pk_mul_f32 v[68:69], v[102:103], v[110:111] op_sel_hi:[1,0]
	v_pk_mul_f32 v[72:73], v[104:105], v[110:111] op_sel_hi:[1,0]
	v_pk_mul_f32 v[76:77], v[98:99], v[110:111] op_sel_hi:[1,0]
	v_pk_fma_f32 v[74:75], v[26:27], v[72:73], v[34:35]
	v_pk_fma_f32 v[72:73], v[24:25], v[68:69], v[32:33]
	v_pk_mul_f32 v[68:69], v[96:97], v[110:111] op_sel_hi:[1,0]
	v_pk_fma_f32 v[78:79], v[22:23], v[76:77], v[30:31]
	v_pk_fma_f32 v[76:77], v[20:21], v[68:69], v[28:29]
	global_store_dwordx4 v[70:71], v[72:75], off offset:2048 nt
	global_store_dwordx4 v[70:71], v[76:79], off offset:2064 nt
	v_pk_mul_f32 v[68:69], v[82:83], v[110:111] op_sel_hi:[1,0]
	v_pk_mul_f32 v[72:73], v[128:129], v[110:111] op_sel_hi:[1,0]
	v_add_co_u32_e32 v82, vcc, s11, v70
	v_pk_fma_f32 v[74:75], v[38:39], v[72:73], v[46:47]
	v_pk_fma_f32 v[72:73], v[36:37], v[68:69], v[44:45]
	v_pk_mul_f32 v[68:69], v[100:101], v[110:111] op_sel_hi:[1,0]
	v_pk_mul_f32 v[76:77], v[132:133], v[110:111] op_sel_hi:[1,0]
	v_addc_co_u32_e32 v83, vcc, 0, v71, vcc
	v_pk_fma_f32 v[78:79], v[42:43], v[76:77], v[50:51]
	v_pk_fma_f32 v[76:77], v[40:41], v[68:69], v[48:49]
	global_store_dwordx4 v[82:83], v[72:75], off nt
	global_store_dwordx4 v[82:83], v[76:79], off offset:16 nt
	v_cmp_lt_i32_e32 vcc, s13, v0
	v_pk_mul_f32 v[72:73], v[80:81], v[110:111] op_sel_hi:[1,0]
	v_pk_mul_f32 v[74:75], v[136:137], v[110:111] op_sel_hi:[1,0]
	v_pk_mul_f32 v[68:69], v[86:87], v[110:111] op_sel_hi:[1,0]
	v_pk_mul_f32 v[70:71], v[140:141], v[110:111] op_sel_hi:[1,0]
	v_pk_fma_f32 v[74:75], v[54:55], v[74:75], v[62:63]
	v_pk_fma_f32 v[72:73], v[52:53], v[72:73], v[60:61]
	s_or_b64 s[2:3], vcc, s[2:3]
	v_pk_fma_f32 v[68:69], v[56:57], v[68:69], v[64:65] op_sel:[0,1,0] op_sel_hi:[1,0,1]
	v_pk_fma_f32 v[70:71], v[58:59], v[70:71], v[66:67] op_sel:[0,1,0] op_sel_hi:[1,0,1]
	global_store_dwordx4 v[82:83], v[72:75], off offset:2048 nt
	global_store_dwordx4 v[82:83], v[68:71], off offset:2064 nt
	s_andn2_b64 exec, exec, s[2:3]
	s_cbranch_execnz .LBB0_31
.LBB0_32:
	s_or_b64 exec, exec, s[0:1]
	s_waitcnt vmcnt(0)
	s_mov_b64 s[4:5], 0
